# XL: XCD-local release for the GEMM->GEMM grid barriers (run-time placement check, full barrier fallback) on top of S2
# baseline (speedup 1.0000x reference)
_Z10fwd_kernel4Args:
	s_load_dword s38, s[0:1], 0x98
	s_load_dwordx4 s[8:11], s[0:1], 0x80
	s_load_dwordx2 s[58:59], s[0:1], 0x90
	s_add_u32 s4, s0, 0x90
	v_and_b32_e32 v178, 0x3ff, v0
	s_addc_u32 s5, s1, 0
	s_waitcnt lgkmcnt(0)
	v_writelane_b32 v253, s8, 0
	v_readfirstlane_b32 s3, v178
	v_cmp_gt_u32_e32 vcc, 2, v178
	v_writelane_b32 v253, s9, 1
	v_writelane_b32 v253, s10, 2
	v_writelane_b32 v253, s11, 3
	s_and_saveexec_b64 s[6:7], vcc
	v_lshl_add_u32 v1, v178, 2, 0
	v_add_u32_e32 v1, 0x20140, v1
	v_mov_b32_e32 v2, 0
	ds_write_b32 v1, v2
	s_or_b64 exec, exec, s[6:7]
	s_load_dwordx4 s[8:11], s[0:1], 0x80
	s_waitcnt lgkmcnt(0)
	s_barrier
	s_getreg_b32 s6, hwreg(HW_REG_XCC_ID, 0, 4)
	s_add_u32 s14, s10, 0x10000
	s_addc_u32 s15, s11, 0
	s_and_b32 s39, s6, 15
	v_cmp_eq_u32_e64 s[94:95], 0, v178
	s_and_saveexec_b64 s[6:7], s[94:95]
	s_cbranch_execz .LBB0_5
	s_mov_b64 s[8:9], exec
	v_mbcnt_lo_u32_b32 v1, s8, 0
	v_mbcnt_hi_u32_b32 v1, s9, v1
	v_cmp_eq_u32_e32 vcc, 0, v1
	s_and_b64 s[10:11], exec, vcc
	s_mov_b64 exec, s[10:11]
	s_cbranch_execz .LBB0_5
	s_lshl_b32 s10, s39, 8
	s_bcnt1_i32_b64 s8, s[8:9]
	v_mov_b32_e32 v1, s10
	v_mov_b32_e32 v2, s8
	global_atomic_add v1, v2, s[14:15] offset:1024
	s_and_b32 s10, s2, 7
	s_lshl_b32 s10, s10, 2
	s_addk_i32 s10, 0x3700
	s_lshl_b32 s8, 1, s39
	v_mov_b32_e32 v1, s10
	v_mov_b32_e32 v2, s8
	global_atomic_or v1, v2, s[14:15]

.LBB0_152:
	s_or_b64 exec, exec, s[0:1]
	s_ashr_i32 s3, s2, 31
	s_cmpk_gt_i32 s2, 0x8ff
	s_cselect_b64 s[96:97], -1, 0
	s_and_b64 s[0:1], s[96:97], exec
	s_movk_i32 s4, 0x200
	s_cselect_b32 s0, 0xfffff700, 0
	s_cselect_b32 s22, s4, 0x120
	s_movk_i32 s4, 0x100
	s_cselect_b32 s1, -1, 0
	s_cselect_b32 s19, 4, 64
	s_cselect_b32 s16, s4, 0x900
	s_add_u32 s0, s0, s2
	s_addc_u32 s1, s1, s3
	s_ashr_i32 s4, s0, 31
	s_lshr_b32 s4, s4, 29
	s_add_i32 s4, s0, s4
	s_ashr_i32 s25, s4, 3
	s_and_b32 s4, s4, -8
	v_readlane_b32 s40, v253, 0
	s_lshr_b32 s23, s16, 3
	s_sub_i32 s26, s0, s4
	s_ashr_i32 s33, s58, 31
	v_readlane_b32 s42, v253, 2
	v_readlane_b32 s43, v253, 3
	s_add_u32 s56, s42, 0x10200
	s_addc_u32 s57, s43, 0
	s_add_u32 s98, s42, 0x10400
	s_addc_u32 s99, s43, 0
	s_add_u32 s100, s42, 0x13700
	s_addc_u32 s101, s43, 0
	v_mov_b32_e32 v234, 0
	s_nop 3
	global_load_dwordx4 v[236:239], v234, s[100:101] sc1
	global_load_dwordx4 v[240:243], v234, s[100:101] offset:16 sc1
	s_waitcnt vmcnt(0)
	v_bcnt_u32_b32 v235, v236, 0
	v_bcnt_u32_b32 v235, v237, v235
	v_bcnt_u32_b32 v235, v238, v235
	v_bcnt_u32_b32 v235, v239, v235
	v_bcnt_u32_b32 v235, v240, v235
	v_bcnt_u32_b32 v235, v241, v235
	v_bcnt_u32_b32 v235, v242, v235
	v_bcnt_u32_b32 v235, v243, v235
	v_or3_b32 v244, v236, v237, v238
	v_or3_b32 v244, v244, v239, v240
	v_or3_b32 v244, v244, v241, v242
	v_or_b32_e32 v244, v244, v243
	v_bcnt_u32_b32 v244, v244, 0
	v_readfirstlane_b32 s100, v235
	v_readfirstlane_b32 s101, v244
	s_cmp_eq_u32 s100, 8
	s_cselect_b32 s100, 1, 0
	s_cmp_eq_u32 s101, 8
	s_cselect_b32 s100, s100, 0
	v_writelane_b32 v255, s100, 45
	s_add_u32 s4, s42, 0x10500
	s_addc_u32 s5, s43, 0
	s_add_u32 s6, s42, 0x10600
	s_addc_u32 s7, s43, 0
	s_add_u32 s8, s42, 0x10700
	s_addc_u32 s9, s43, 0
	v_readlane_b32 s41, v253, 1
	v_writelane_b32 v253, s8, 36
	v_cvt_f32_u32_e32 v0, s22
	v_mov_b32_e32 v1, 0
	v_writelane_b32 v253, s9, 37
	s_add_u32 s8, s42, 0x10800
	s_addc_u32 s9, s43, 0
	v_writelane_b32 v253, s8, 38
	v_rcp_iflag_f32_e32 v0, v0
	s_mul_i32 s59, s59, s58
	v_writelane_b32 v253, s9, 39
	s_add_u32 s8, s42, 0x10900
	s_addc_u32 s9, s43, 0
	v_writelane_b32 v253, s8, 40
	v_mul_f32_e32 v0, 0x4f7ffffe, v0
	v_cvt_u32_f32_e32 v0, v0
	v_writelane_b32 v253, s9, 41
	s_add_u32 s8, s42, 0x10a00
	s_addc_u32 s9, s43, 0
	v_writelane_b32 v253, s8, 42
	v_readfirstlane_b32 s35, v0
	v_mov_b64_e32 v[180:181], 0x100
	v_writelane_b32 v253, s9, 43
	s_add_u32 s8, s42, 0x10b00
	s_addc_u32 s9, s43, 0
	v_writelane_b32 v253, s8, 44
	s_mul_i32 s59, s59, s38
	v_mov_b32_e32 v211, 0x358637bd
	v_writelane_b32 v253, s9, 45
	s_add_u32 s8, s42, 0x10c00
	s_addc_u32 s9, s43, 0
	v_writelane_b32 v253, s8, 46
	v_mov_b32_e32 v252, 1
	v_mov_b64_e32 v[182:183], 0x8ff
	v_writelane_b32 v253, s9, 47
	s_add_u32 s8, s42, 0x10d00
	s_addc_u32 s9, s43, 0
	v_writelane_b32 v253, s8, 48
	v_mov_b32_e32 v216, 0x3e38aa3b
	v_mbcnt_hi_u32_b32 v217, -1, v12
	v_writelane_b32 v253, s9, 49
	s_add_u32 s8, s42, 0x10e00
	s_addc_u32 s9, s43, 0
	v_writelane_b32 v253, s8, 50
	v_mov_b32_e32 v218, 0x7f800000
	v_mov_b64_e32 v[184:185], 0xff
	v_writelane_b32 v253, s9, 51
	s_add_u32 s8, s42, 0x10f00
	s_addc_u32 s9, s43, 0
	v_writelane_b32 v253, s8, 52
	s_barrier
	s_nop 0
	v_writelane_b32 v253, s9, 53
	s_add_u32 s8, s42, 0x11000
	s_addc_u32 s9, s43, 0
	v_writelane_b32 v253, s8, 54
	s_nop 1
	v_writelane_b32 v253, s9, 55
	s_add_u32 s8, s42, 0x11100
	s_addc_u32 s9, s43, 0
	v_writelane_b32 v253, s8, 56
	s_nop 1
	v_writelane_b32 v253, s9, 57
	s_add_u32 s8, s42, 0x11200
	s_addc_u32 s9, s43, 0
	s_add_u32 s12, s42, 0x11300
	s_addc_u32 s13, s43, 0
	v_writelane_b32 v253, s8, 58
	s_cmp_eq_u32 s39, 15
	s_nop 0
	v_writelane_b32 v253, s9, 59
	s_cselect_b64 s[8:9], -1, 0
	v_writelane_b32 v253, s8, 60
	s_cmp_eq_u32 s39, 14
	s_nop 0
	v_writelane_b32 v253, s9, 61
	s_cselect_b64 s[8:9], -1, 0
	v_writelane_b32 v253, s8, 62
	s_cmp_eq_u32 s39, 13
	s_nop 0
	v_writelane_b32 v253, s9, 63
	s_cselect_b64 s[8:9], -1, 0
	v_writelane_b32 v254, s8, 0
	s_cmp_eq_u32 s39, 12
	s_nop 0
	v_writelane_b32 v254, s9, 1
	s_cselect_b64 s[8:9], -1, 0
	v_writelane_b32 v254, s8, 2
	s_cmp_eq_u32 s39, 11
	s_nop 0
	v_writelane_b32 v254, s9, 3
	s_cselect_b64 s[8:9], -1, 0
	v_writelane_b32 v254, s8, 4
	s_cmp_eq_u32 s39, 10
	s_nop 0
	v_writelane_b32 v254, s9, 5
	s_cselect_b64 s[8:9], -1, 0
	v_writelane_b32 v254, s8, 6
	s_cmp_eq_u32 s39, 9
	s_nop 0
	v_writelane_b32 v254, s9, 7
	s_cselect_b64 s[8:9], -1, 0
	v_writelane_b32 v254, s8, 8
	s_cmp_eq_u32 s39, 8
	s_nop 0
	v_writelane_b32 v254, s9, 9
	s_cselect_b64 s[8:9], -1, 0
	v_writelane_b32 v254, s8, 10
	s_cmp_eq_u32 s39, 7
	s_nop 0
	v_writelane_b32 v254, s9, 11
	s_cselect_b64 s[8:9], -1, 0
	v_writelane_b32 v254, s8, 12
	s_cmp_eq_u32 s39, 6
	s_nop 0
	v_writelane_b32 v254, s9, 13
	s_cselect_b64 s[8:9], -1, 0
	v_writelane_b32 v254, s8, 14
	s_cmp_eq_u32 s39, 5
	s_nop 0
	v_writelane_b32 v254, s9, 15
	s_cselect_b64 s[8:9], -1, 0
	v_writelane_b32 v254, s8, 16
	s_cmp_eq_u32 s39, 4
	s_nop 0
	v_writelane_b32 v254, s9, 17
	s_cselect_b64 s[8:9], -1, 0
	v_writelane_b32 v254, s8, 18
	s_cmp_eq_u32 s39, 3
	s_nop 0
	v_writelane_b32 v254, s9, 19
	s_cselect_b64 s[8:9], -1, 0
	v_writelane_b32 v254, s8, 20
	s_cmp_eq_u32 s39, 2
	s_nop 0
	v_writelane_b32 v254, s9, 21
	s_cselect_b64 s[8:9], -1, 0
	v_writelane_b32 v254, s8, 22
	s_cmp_eq_u32 s39, 1
	s_nop 0
	v_writelane_b32 v254, s9, 23
	s_cselect_b64 s[8:9], -1, 0
	v_writelane_b32 v254, s8, 24
	s_cmp_eq_u32 s39, 0
	s_nop 0
	v_writelane_b32 v254, s9, 25
	s_cselect_b64 s[8:9], -1, 0
	s_lshl_b32 s17, s39, 8
	s_add_u32 s14, s14, s17
	v_writelane_b32 v254, s8, 26
	s_addc_u32 s15, s15, 0
	s_mov_b64 s[38:39], s[6:7]
	v_writelane_b32 v254, s9, 27
	s_add_u32 s8, s14, 0x1400
	s_addc_u32 s9, s15, 0
	v_writelane_b32 v254, s8, 28
	s_nop 1
	v_writelane_b32 v254, s9, 29
	s_add_u32 s8, s14, 0x2400
	s_addc_u32 s9, s15, 0
	v_writelane_b32 v254, s8, 30
	s_nop 1
	v_writelane_b32 v254, s9, 31
	s_add_u32 s8, s42, 0x13400
	s_addc_u32 s9, s43, 0
	v_writelane_b32 v254, s8, 32
	s_nop 1
	v_writelane_b32 v254, s9, 33
	s_add_u32 s8, s42, 0x13500
	s_addc_u32 s9, s43, 0
	v_writelane_b32 v254, s8, 34
	s_add_i32 s14, s58, 7
	s_ashr_i32 s64, s14, 3
	v_writelane_b32 v254, s9, 35
	s_lshl_b32 s8, s2, 9
	s_lshl_b32 s93, s58, 9
	s_and_b32 s24, s2, 7
	s_ashr_i32 s55, s2, 3
	s_cmp_lt_i32 s55, 32
	s_cselect_b64 s[20:21], -1, 0
	s_lshl_b32 s14, s55, 1
	s_and_b32 s14, s14, 62
	s_lshl_b32 s17, s14, 16
	s_lshl_b32 s34, s14, 6
	s_lshl_b32 s67, s24, 7
	s_or_b32 s18, s17, 0x10000
	s_or_b32 s65, s34, 63
	s_cmpk_gt_i32 s2, 0xff
	v_writelane_b32 v254, s8, 36
	s_cselect_b64 s[8:9], -1, 0
	v_writelane_b32 v254, s8, 37
	s_and_b64 s[14:15], s[8:9], exec
	s_cselect_b32 s14, 0xffffff00, 0
	s_cselect_b32 s15, -1, 0
	s_add_u32 s14, s14, s2
	s_addc_u32 s15, s15, s3
	s_ashr_i32 s27, s14, 31
	s_lshr_b32 s27, s27, 29
	s_add_i32 s27, s14, s27
	s_ashr_i32 s28, s27, 3
	s_and_b32 s27, s27, -8
	s_sub_i32 s27, s14, s27
	s_lshl_b32 s29, s27, 5
	s_cmpk_lt_i32 s2, 0x100
	v_writelane_b32 v254, s9, 38
	s_cselect_b64 s[8:9], -1, 0
	s_lshr_b32 s30, s26, 31
	s_or_b32 s23, s23, s30
	s_mul_i32 s23, s26, s23
	s_add_i32 s23, s23, s25
	s_lshr_b32 s25, s3, 29
	s_add_i32 s25, s2, s25
	s_ashr_i32 s26, s25, 3
	s_and_b32 s25, s25, -8
	s_sub_i32 s25, s2, s25
	s_lshl_b32 s30, s25, 5
	s_cmp_lt_i32 s27, 0
	s_mul_i32 s27, s27, 33
	s_cselect_b32 s27, s27, s29
	s_add_i32 s27, s27, s28
	s_ashr_i32 s28, s27, 31
	s_lshr_b32 s28, s28, 27
	s_add_i32 s28, s27, s28
	s_and_b32 s29, s28, 0xffffffe0
	s_sub_i32 s29, s27, s29
	s_ashr_i32 s27, s28, 5
	s_lshl_b32 s28, s27, 3
	s_sub_i32 s27, 64, s28
	s_min_i32 s31, s27, 8
	s_cmp_lt_i32 s25, 0
	s_mul_i32 s25, s25, 33
	s_cselect_b32 s25, s25, s30
	s_add_i32 s25, s25, s26
	s_ashr_i32 s26, s25, 31
	s_lshr_b32 s26, s26, 27
	s_add_i32 s26, s25, s26
	s_and_b32 s27, s26, 0xffe0
	s_sub_i32 s25, s25, s27
	s_bfe_i32 s27, s25, 0x80000
	s_bfe_u32 s27, s27, 0x3000c
	s_add_i32 s27, s25, s27
	s_and_b32 s30, s27, 0xf8
	s_sub_i32 s25, s25, s30
	s_ashr_i32 s26, s26, 5
	s_bfe_i32 s27, s27, 0x80000
	s_sub_i32 s30, 0, s22
	s_lshl_b32 s26, s26, 3
	s_sext_i32_i16 s27, s27
	s_sext_i32_i8 s25, s25
	v_writelane_b32 v254, s8, 39
	s_mul_i32 s30, s30, s35
	s_add_i32 s10, s26, s25
	s_lshr_b32 s26, s27, 3
	v_writelane_b32 v254, s9, 40
	s_mul_hi_u32 s30, s35, s30
	s_ashr_i32 s8, s27, 3
	s_bfe_i64 s[26:27], s[26:27], 0x100000
	s_add_i32 s35, s35, s30
	s_abs_i32 s30, s23
	v_writelane_b32 v254, s8, 41
	s_lshl_b64 s[8:9], s[26:27], 19
	s_mul_hi_u32 s35, s30, s35
	v_writelane_b32 v254, s8, 42
	s_mul_i32 s36, s35, s22
	s_sub_i32 s30, s30, s36
	v_writelane_b32 v254, s9, 43
	s_mov_b32 s8, s10
	s_ashr_i32 s11, s10, 31
	v_writelane_b32 v254, s8, 44
	s_ashr_i32 s25, s23, 31
	s_add_i32 s26, s35, 1
	s_sub_i32 s27, s30, s22
	v_writelane_b32 v254, s9, 45
	s_lshl_b64 s[8:9], s[10:11], 19
	s_cmp_ge_u32 s30, s22
	s_cselect_b32 s26, s26, s35
	s_cselect_b32 s27, s27, s30
	s_add_i32 s30, s26, 1
	s_cmp_ge_u32 s27, s22
	s_cselect_b32 s26, s30, s26
	s_xor_b32 s26, s26, s25
	s_sub_i32 s25, s26, s25
	s_mul_i32 s22, s25, s22
	s_sub_i32 s22, s23, s22
	s_lshl_b32 s23, s25, 3
	s_sub_i32 s19, s19, s23
	s_min_i32 s19, s19, 8
	s_abs_i32 s25, s19
	v_cvt_f32_u32_e32 v0, s25
	s_sub_i32 s26, 0, s25
	v_writelane_b32 v254, s8, 46
	v_cmp_lt_i64_e64 s[6:7], s[14:15], v[180:181]
	v_rcp_iflag_f32_e32 v0, v0
	v_writelane_b32 v254, s9, 47
	v_mul_f32_e32 v0, 0x4f7ffffe, v0
	v_cvt_u32_f32_e32 v0, v0
	s_nop 0
	v_readfirstlane_b32 s27, v0
	s_mul_i32 s26, s26, s27
	s_mul_hi_u32 s26, s27, s26
	s_add_i32 s27, s27, s26
	s_abs_i32 s26, s22
	s_mul_hi_u32 s27, s26, s27
	s_mul_i32 s30, s27, s25
	s_sub_i32 s26, s26, s30
	s_xor_b32 s30, s22, s19
	s_ashr_i32 s30, s30, 31
	s_add_i32 s35, s27, 1
	s_sub_i32 s36, s26, s25
	s_cmp_ge_u32 s26, s25
	s_cselect_b32 s27, s35, s27
	s_cselect_b32 s26, s36, s26
	s_add_i32 s35, s27, 1
	s_cmp_ge_u32 s26, s25
	s_cselect_b32 s25, s35, s27
	s_xor_b32 s25, s25, s30
	s_sub_i32 s8, s25, s30
	s_mul_i32 s19, s8, s19
	s_sub_i32 s19, s22, s19
	v_writelane_b32 v254, s8, 48
	s_add_i32 s8, s19, s23
	s_abs_i32 s19, s31
	v_cvt_f32_u32_e32 v0, s19
	s_sub_i32 s22, 0, s19
	v_writelane_b32 v254, s8, 49
	v_rcp_iflag_f32_e32 v0, v0
	s_nop 0
	v_mul_f32_e32 v0, 0x4f7ffffe, v0
	v_cvt_u32_f32_e32 v0, v0
	s_nop 0
	v_readfirstlane_b32 s23, v0
	s_mul_i32 s22, s22, s23
	s_mul_hi_u32 s22, s23, s22
	s_add_i32 s23, s23, s22
	s_abs_i32 s22, s29
	s_mul_hi_u32 s23, s22, s23
	s_mul_i32 s25, s23, s19
	s_sub_i32 s22, s22, s25
	s_xor_b32 s25, s29, s31
	s_ashr_i32 s25, s25, 31
	s_add_i32 s26, s23, 1
	s_sub_i32 s27, s22, s19
	s_cmp_ge_u32 s22, s19
	s_cselect_b32 s23, s26, s23
	v_mov_b32_e32 v0, s16
	s_cselect_b32 s22, s27, s22
	s_add_i32 s26, s23, 1
	v_cmp_lt_i64_e64 s[0:1], s[0:1], v[0:1]
	s_cmp_ge_u32 s22, s19
	s_nop 0
	v_writelane_b32 v254, s0, 50
	s_nop 1
	v_writelane_b32 v254, s1, 51
	v_cndmask_b32_e64 v179, 0, 1, s[0:1]
	s_cselect_b32 s0, s26, s23
	s_xor_b32 s0, s0, s25
	s_sub_i32 s8, s0, s25
	s_mul_i32 s0, s8, s31
	v_writelane_b32 v254, s6, 52
	s_sub_i32 s0, s29, s0
	s_lshl_b32 s1, s2, 12
	v_writelane_b32 v254, s7, 53
	s_add_i32 s10, s28, s0
	v_writelane_b32 v254, s1, 54
	s_lshl_b32 s1, s58, 12
	v_writelane_b32 v254, s1, 55
	s_mov_b32 s6, s10
	s_ashr_i32 s11, s10, 31
	v_writelane_b32 v254, s6, 56
	s_ashr_i32 s9, s8, 31
	s_mul_i32 s0, s24, 0x280
	v_writelane_b32 v254, s7, 57
	s_lshl_b64 s[6:7], s[10:11], 19
	v_writelane_b32 v254, s6, 58
	s_mulk_i32 s24, 0xa00
	s_mov_b32 s23, 0
	v_writelane_b32 v254, s7, 59
	s_mov_b32 s6, s8
	v_writelane_b32 v254, s6, 60
	s_mov_b32 s35, s23
	s_mov_b64 s[10:11], 0x80
	v_writelane_b32 v254, s7, 61
	s_lshl_b64 s[6:7], s[8:9], 19
	s_add_u32 s1, s42, s24
	s_addc_u32 s14, s43, 0
	s_add_u32 s1, s1, 0x100
	v_writelane_b32 v255, s1, 0
	s_addc_u32 s1, s14, 0
	v_writelane_b32 v255, s1, 1
	s_lshl_b32 s0, s0, 2
	v_writelane_b32 v255, s0, 2
	s_add_i32 s0, 0, 0x20140
	v_writelane_b32 v255, s0, 3
	s_add_i32 s0, 0, 0x20144
	v_writelane_b32 v255, s0, 4
	v_writelane_b32 v255, s94, 5
	s_and_b32 s1, s55, 31
	v_writelane_b32 v254, s6, 62
	v_writelane_b32 v255, s95, 6
	v_writelane_b32 v255, s4, 7
	s_lshl_b32 s82, s1, 17
	v_writelane_b32 v254, s7, 63
	v_writelane_b32 v255, s5, 8
	v_writelane_b32 v255, s38, 9
	s_lshl_b32 s66, s1, 7
	s_add_i32 s82, s82, 0x30000
	v_writelane_b32 v255, s39, 10
	v_writelane_b32 v255, s93, 11
	v_writelane_b32 v255, s56, 12
	s_add_i32 s83, 0, 0x11800
	s_add_i32 s68, 0, 0x11000
	v_writelane_b32 v255, s57, 13
	v_writelane_b32 v255, s98, 14
	s_lshl_b32 s28, s17, 1
	s_lshl_b32 s30, s18, 1
	v_writelane_b32 v255, s99, 15
	v_writelane_b32 v255, s96, 16
	s_mov_b32 s6, 0
	s_nop 0
	v_writelane_b32 v255, s97, 17
	s_branch .LBB0_154

.LBB0_409:
	s_andn2_saveexec_b64 s[14:15], s[14:15]
	s_cbranch_execz .LBB0_429
	s_mov_b64 s[14:15], exec
	v_readlane_b32 s100, v255, 45
	s_cmp_lg_u32 s100, 0
	s_cbranch_scc1 .LBB0_426
	buffer_wbl2 sc1
	s_waitcnt lgkmcnt(0)
	s_waitcnt vmcnt(0)
	v_mbcnt_lo_u32_b32 v0, s14, 0
	v_mbcnt_hi_u32_b32 v0, s15, v0
	v_cmp_eq_u32_e32 vcc, 0, v0
	s_and_saveexec_b64 s[16:17], vcc
	s_cbranch_execz .LBB0_412
	s_bcnt1_i32_b64 s14, s[14:15]
	v_readlane_b32 s8, v254, 32
	v_mov_b32_e32 v3, s14
	v_readlane_b32 s9, v254, 33
	s_nop 4
	global_atomic_add v3, v1, v3, s[8:9] sc0
